# on top of previous: grid barrier waits on the cross-XCD arrival counter reaching (generation+1)*nx instead of a separately published generation word
# baseline (speedup 1.0000x reference)
; DI unsigned xb_ld(unsigned* p)              { return __hip_atomic_load(p, __ATOMIC_RELAXED, __HIP_MEMORY_SCOPE_AGENT); }
; DI unsigned xb_add(unsigned* p, unsigned v) { return __hip_atomic_fetch_add(p, v, __ATOMIC_RELAXED, __HIP_MEMORY_SCOPE_AGENT); }
; #define XB_SPIN(cond, bar) do { unsigned _sp = 0; while (cond) { __builtin_amdgcn_s_sleep(1); \
;     if ((++_sp & 255u) == 0u) { if (xb_ld(&(bar)[XB_TMO])) break; if (_sp > XB_SPIN_CAP) { atomicAdd(&(bar)[XB_TMO], 1u); break; } } } } while (0)
; DI void xcd_barrier(const XcdBarrier& b) {
;     ...
;         const unsigned old = xb_add(&bar[XB_XSUB(b.x)], 1u);
;         const unsigned gen = old / nloc;
;         if (old + 1u == (gen + 1u) * nloc) {
;             __builtin_amdgcn_fence(__ATOMIC_RELEASE, "agent");
;             asm volatile("s_waitcnt vmcnt(0)" ::: "memory");
;             const unsigned og = xb_add(&bar[XB_TOP], 1u);
;             const unsigned tg = og / nx;
;             if (og + 1u == (tg + 1u) * nx) xb_add(&bar[XB_TOPGEN], 1u);
;             else XB_SPIN(xb_ld(&bar[XB_TOPGEN]) == tg, bar);
;             __builtin_amdgcn_fence(__ATOMIC_ACQUIRE, "agent");
;             xb_add(&bar[XB_XGEN(b.x)], 1u);
;             asm volatile("s_waitcnt vmcnt(0)" ::: "memory");
;         } else {
;             XB_SPIN(xb_ld(&bar[XB_XGEN(b.x)]) == gen, bar);
.LBB0_965:
	s_or_b64 exec, exec, s[4:5]
	v_cvt_f32_u32_e32 v5, v3
	s_waitcnt vmcnt(0)
	v_readfirstlane_b32 s4, v4
	v_sub_u32_e32 v4, 0, v3
	v_rcp_iflag_f32_e32 v5, v5
	v_add_u32_e32 v6, s4, v0
	v_mul_f32_e32 v5, 0x4f7ffffe, v5
	v_cvt_u32_f32_e32 v5, v5
	v_mul_lo_u32 v0, v4, v5
	v_mul_hi_u32 v0, v5, v0
	v_add_u32_e32 v0, v5, v0
	v_mul_hi_u32 v0, v6, v0
	v_mul_lo_u32 v4, v0, v3
	v_sub_u32_e32 v4, v6, v4
	v_add_u32_e32 v5, 1, v0
	v_cmp_ge_u32_e32 vcc, v4, v3
	s_nop 1
	v_cndmask_b32_e32 v0, v0, v5, vcc
	v_sub_u32_e32 v5, v4, v3
	v_cndmask_b32_e32 v4, v4, v5, vcc
	v_add_u32_e32 v5, 1, v0
	v_cmp_ge_u32_e32 vcc, v4, v3
	v_add_u32_e32 v4, 1, v6
	s_nop 0
	v_cndmask_b32_e32 v0, v0, v5, vcc
	v_mul_lo_u32 v5, v3, v0
	v_add_u32_e32 v3, v5, v3
	v_cmp_ne_u32_e32 vcc, v4, v3
	s_and_saveexec_b64 s[4:5], vcc
	s_xor_b64 s[4:5], exec, s[4:5]
	s_cbranch_execz .LBB0_979
	v_add_u32_e32 v7, 1, v0
	v_mul_lo_u32 v7, v7, v2
	v_readlane_b32 s6, v252, 61
	v_readlane_b32 s7, v252, 62
	s_waitcnt lgkmcnt(0)
	s_nop 3
	global_load_dword v2, v1, s[6:7] sc1
	s_waitcnt vmcnt(0)
	v_cmp_lt_u32_e32 vcc, v2, v7
	s_and_saveexec_b64 s[6:7], vcc
	s_cbranch_execz .LBB0_978
	s_mov_b32 s19, 1
	s_mov_b64 s[8:9], 0
	s_branch .LBB0_969

; DI unsigned xb_ld(unsigned* p)              { return __hip_atomic_load(p, __ATOMIC_RELAXED, __HIP_MEMORY_SCOPE_AGENT); }
; DI unsigned xb_add(unsigned* p, unsigned v) { return __hip_atomic_fetch_add(p, v, __ATOMIC_RELAXED, __HIP_MEMORY_SCOPE_AGENT); }
; #define XB_SPIN(cond, bar) do { unsigned _sp = 0; while (cond) { __builtin_amdgcn_s_sleep(1); \
;     if ((++_sp & 255u) == 0u) { if (xb_ld(&(bar)[XB_TMO])) break; if (_sp > XB_SPIN_CAP) { atomicAdd(&(bar)[XB_TMO], 1u); break; } } } } while (0)
; DI void xcd_barrier(const XcdBarrier& b) {
;     ...
;             else XB_SPIN(xb_ld(&bar[XB_TOPGEN]) == tg, bar);
;             __builtin_amdgcn_fence(__ATOMIC_ACQUIRE, "agent");
;             xb_add(&bar[XB_XGEN(b.x)], 1u);
;             asm volatile("s_waitcnt vmcnt(0)" ::: "memory");
;         } else {
;             XB_SPIN(xb_ld(&bar[XB_XGEN(b.x)]) == gen, bar);
.LBB0_973:
	v_readlane_b32 s12, v252, 61
	v_readlane_b32 s13, v252, 62
	s_add_i32 s19, s19, 1
	s_mov_b64 s[14:15], -1
	s_nop 2
	global_load_dword v2, v1, s[12:13] sc1
	s_waitcnt vmcnt(0)
	v_cmp_ge_u32_e32 vcc, v2, v7
	s_orn2_b64 s[12:13], vcc, exec
	s_branch .LBB0_968

; DI unsigned xb_ld(unsigned* p)              { return __hip_atomic_load(p, __ATOMIC_RELAXED, __HIP_MEMORY_SCOPE_AGENT); }
; DI unsigned xb_add(unsigned* p, unsigned v) { return __hip_atomic_fetch_add(p, v, __ATOMIC_RELAXED, __HIP_MEMORY_SCOPE_AGENT); }
; #define XB_SPIN(cond, bar) do { unsigned _sp = 0; while (cond) { __builtin_amdgcn_s_sleep(1); \
;     if ((++_sp & 255u) == 0u) { if (xb_ld(&(bar)[XB_TMO])) break; if (_sp > XB_SPIN_CAP) { atomicAdd(&(bar)[XB_TMO], 1u); break; } } } } while (0)
; DI void xcd_barrier(const XcdBarrier& b) {
;     ...
;         const unsigned old = xb_add(&bar[XB_XSUB(b.x)], 1u);
;         const unsigned gen = old / nloc;
;         if (old + 1u == (gen + 1u) * nloc) {
;             __builtin_amdgcn_fence(__ATOMIC_RELEASE, "agent");
;             asm volatile("s_waitcnt vmcnt(0)" ::: "memory");
;             const unsigned og = xb_add(&bar[XB_TOP], 1u);
;             const unsigned tg = og / nx;
;             if (og + 1u == (tg + 1u) * nx) xb_add(&bar[XB_TOPGEN], 1u);
;             else XB_SPIN(xb_ld(&bar[XB_TOPGEN]) == tg, bar);
;             __builtin_amdgcn_fence(__ATOMIC_ACQUIRE, "agent");
;             xb_add(&bar[XB_XGEN(b.x)], 1u);
;             asm volatile("s_waitcnt vmcnt(0)" ::: "memory");
;         } else {
;             XB_SPIN(xb_ld(&bar[XB_XGEN(b.x)]) == gen, bar);
.LBB0_982:
	s_or_b64 exec, exec, s[6:7]
	s_waitcnt vmcnt(0)
	v_readfirstlane_b32 s4, v3
	v_sub_u32_e32 v4, 0, v2
	s_mov_b64 s[6:7], -1
	v_add_u32_e32 v3, s4, v0
	v_cvt_f32_u32_e32 v0, v2
	v_readlane_b32 s4, v252, 63
	v_readlane_b32 s5, v253, 0
	v_rcp_iflag_f32_e32 v0, v0
	s_nop 0
	v_mul_f32_e32 v0, 0x4f7ffffe, v0
	v_cvt_u32_f32_e32 v0, v0
	v_mul_lo_u32 v4, v4, v0
	v_mul_hi_u32 v4, v0, v4
	v_add_u32_e32 v0, v0, v4
	v_mul_hi_u32 v0, v3, v0
	v_mul_lo_u32 v4, v0, v2
	v_sub_u32_e32 v4, v3, v4
	v_cmp_ge_u32_e32 vcc, v4, v2
	v_add_u32_e32 v5, 1, v0
	v_add_u32_e32 v3, 1, v3
	v_cndmask_b32_e32 v0, v0, v5, vcc
	v_sub_u32_e32 v5, v4, v2
	v_cndmask_b32_e32 v4, v4, v5, vcc
	v_cmp_ge_u32_e32 vcc, v4, v2
	v_add_u32_e32 v4, 1, v0
	s_nop 0
	v_cndmask_b32_e32 v0, v0, v4, vcc
	v_mul_lo_u32 v4, v2, v0
	v_add_u32_e32 v2, v4, v2
	v_mov_b32_e32 v7, v2
	v_cmp_ne_u32_e32 vcc, v3, v2
	v_mov_b64_e32 v[2:3], s[4:5]
	s_and_saveexec_b64 s[4:5], vcc
	s_cbranch_execz .LBB0_998
	v_readlane_b32 s6, v252, 61
	v_readlane_b32 s7, v252, 62
	s_mov_b64 s[8:9], 0
	s_nop 3
	global_load_dword v2, v1, s[6:7] sc1
	s_waitcnt vmcnt(0)
	v_cmp_lt_u32_e32 vcc, v2, v7
	s_and_saveexec_b64 s[6:7], vcc
	s_cbranch_execz .LBB0_997
	s_mov_b32 s19, 1
	s_branch .LBB0_986
